# branch-GEMM gate epilogue: compiler vmcnt(0) waits replaced by counted vmcnt per 8-value block (gate loads stay in flight behind the VALU)
# speedup vs baseline: 1.0102x; 1.0102x over previous
.LBB0_114:
	s_lshl_b32 s22, s52, 4
	s_lshl_b32 s28, s26, 5
	s_add_i32 s22, s22, s20
	s_ashr_i32 s29, s28, 31
	s_lshl_b32 s27, s55, 3
	s_ashr_i32 s23, s22, 31
	s_ashr_i32 s30, s27, 31
	s_or_b64 s[28:29], s[28:29], s[0:1]
	s_add_u32 s28, s28, s27
	s_addc_u32 s29, s29, s30
	s_lshl_b64 s[22:23], s[22:23], 17
	s_lshl_b64 s[28:29], s[28:29], 10
	s_add_u32 s22, s78, s22
	s_addc_u32 s23, s79, s23
	s_add_u32 s22, s22, s28
	s_addc_u32 s23, s23, s29
	v_mov_b32_e32 v100, v245
	s_cmp_eq_u32 s26, 3
	s_cselect_b64 s[36:37], -1, 0
	v_ashrrev_i32_e32 v101, 31, v100
	v_lshl_add_u64 v[208:209], v[100:101], 4, s[22:23]
	s_and_b64 s[28:29], s[36:37], exec
	global_load_dwordx4 v[198:201], v[208:209], off
	s_cselect_b32 s27, 0, 0x800
	s_lshl_b32 s88, s27, 4
	v_lshl_add_u64 v[100:101], v[208:209], 0, s[88:89]
	global_load_dwordx4 v[202:205], v[100:101], off
	s_mov_b64 s[22:23], 0x20000
	v_lshl_add_u64 v[100:101], v[208:209], 0, s[22:23]
	s_mov_b32 s22, 0x21000
	v_add_co_u32_e32 v102, vcc, s22, v208
	v_lshl_add_u64 v[100:101], v[100:101], 0, s[88:89]
	s_nop 0
	v_addc_co_u32_e32 v103, vcc, 0, v209, vcc
	s_mov_b64 s[22:23], 0x40000
	global_load_dwordx4 v[180:183], v[102:103], off offset:-4096
	global_load_dwordx4 v[176:179], v[100:101], off
	v_lshl_add_u64 v[100:101], v[208:209], 0, s[22:23]
	s_mov_b32 s22, 0x41000
	v_lshl_add_u64 v[100:101], v[100:101], 0, s[88:89]
	v_add_co_u32_e32 v104, vcc, s22, v208
	global_load_dwordx4 v[172:175], v[100:101], off
	global_load_dwordx4 v[140:143], v[102:103], off
	v_lshl_add_u64 v[100:101], v[208:209], 0, s[82:83]
	v_addc_co_u32_e32 v105, vcc, 0, v209, vcc
	v_lshl_add_u64 v[100:101], v[100:101], 0, s[88:89]
	global_load_dwordx4 v[168:171], v[104:105], off offset:-4096
	global_load_dwordx4 v[160:163], v[100:101], off
	s_mov_b32 s22, 0x61000
	v_lshl_add_u64 v[100:101], v[208:209], 0, s[94:95]
	v_add_co_u32_e32 v106, vcc, s22, v208
	v_lshl_add_u64 v[100:101], v[100:101], 0, s[88:89]
	s_mov_b64 s[22:23], 0x21000
	global_load_dwordx4 v[152:155], v[100:101], off
	global_load_dwordx4 v[120:123], v[104:105], off
	v_lshl_add_u64 v[100:101], v[208:209], 0, s[22:23]
	v_addc_co_u32_e32 v107, vcc, 0, v209, vcc
	s_movk_i32 s4, 0x1000
	v_lshl_add_u64 v[100:101], v[100:101], 0, s[88:89]
	s_mov_b64 s[22:23], 0x41000
	global_load_dwordx4 v[164:167], v[106:107], off offset:-4096
	global_load_dwordx4 v[132:135], v[100:101], off
	v_add_co_u32_e32 v116, vcc, s4, v208
	v_lshl_add_u64 v[100:101], v[208:209], 0, s[22:23]
	s_nop 0
	v_addc_co_u32_e32 v117, vcc, 0, v209, vcc
	v_lshl_add_u64 v[100:101], v[100:101], 0, s[88:89]
	s_mov_b64 s[22:23], 0x61000
	global_load_dwordx4 v[156:159], v[116:117], off
	s_movk_i32 s33, 0x3fff
	global_load_dwordx4 v[116:119], v[100:101], off
	s_cmp_lg_u32 s26, 3
	global_load_dwordx4 v[104:107], v[106:107], off
	v_lshl_add_u64 v[100:101], v[208:209], 0, s[22:23]
	v_lshl_add_u64 v[100:101], v[100:101], 0, s[88:89]
	global_load_dwordx4 v[100:103], v[100:101], off
	v_lshl_add_u32 v216, s52, 8, v242
	s_waitcnt vmcnt(14)
	v_lshlrev_b32_e32 v206, 16, v198
	v_and_b32_e32 v207, 0xffff0000, v198
	v_rcp_f32_e32 v206, v206
	v_rcp_f32_e32 v207, v207
	v_lshlrev_b32_e32 v210, 16, v199
	v_and_b32_e32 v211, 0xffff0000, v199
	v_lshlrev_b32_e32 v198, 16, v202
	v_and_b32_e32 v199, 0xffff0000, v202
	v_pk_mul_f32 v[198:199], v[206:207], v[198:199]
	v_lshlrev_b32_e32 v212, 16, v200
	v_cndmask_b32_e64 v199, v199, v207, s[36:37]
	v_cndmask_b32_e64 v198, v198, v206, s[36:37]
	v_pk_mul_f32 v[198:199], v[148:149], v[198:199]
	v_rcp_f32_e32 v148, v210
	v_rcp_f32_e32 v149, v211
	v_and_b32_e32 v213, 0xffff0000, v200
	v_lshlrev_b32_e32 v214, 16, v201
	v_and_b32_e32 v215, 0xffff0000, v201
	v_lshlrev_b32_e32 v200, 16, v203
	v_and_b32_e32 v201, 0xffff0000, v203
	v_pk_mul_f32 v[200:201], v[148:149], v[200:201]
	v_lshlrev_b32_e32 v202, 16, v204
	v_cndmask_b32_e64 v149, v201, v149, s[36:37]
	v_cndmask_b32_e64 v148, v200, v148, s[36:37]
	v_pk_mul_f32 v[200:201], v[150:151], v[148:149]
	v_rcp_f32_e32 v148, v212
	v_rcp_f32_e32 v149, v213
	v_and_b32_e32 v203, 0xffff0000, v204
	v_lshlrev_b32_e32 v204, 16, v205
	v_and_b32_e32 v205, 0xffff0000, v205
	v_pk_mul_f32 v[150:151], v[148:149], v[202:203]
	v_lshl_or_b32 v206, s55, 8, v192
	v_cndmask_b32_e64 v149, v151, v149, s[36:37]
	v_cndmask_b32_e64 v148, v150, v148, s[36:37]
	v_pk_mul_f32 v[202:203], v[144:145], v[148:149]
	v_rcp_f32_e32 v144, v214
	v_rcp_f32_e32 v145, v215
	s_nop 0
	v_pk_mul_f32 v[148:149], v[144:145], v[204:205]
	s_nop 0
	v_cndmask_b32_e64 v145, v149, v145, s[36:37]
	v_cndmask_b32_e64 v144, v148, v144, s[36:37]
	v_pk_mul_f32 v[204:205], v[146:147], v[144:145]
	s_cbranch_scc1 .LBB0_116
	v_ashrrev_i32_e32 v217, 31, v216
	v_readlane_b32 s4, v253, 16
	v_lshlrev_b64 v[148:149], 11, v[216:217]
	v_readlane_b32 s6, v253, 18
	v_readlane_b32 s7, v253, 19
	v_ashrrev_i32_e32 v207, 31, v206
	v_cvt_pk_bf16_f32 v144, v198, v199
	v_cvt_pk_bf16_f32 v145, v200, v201
	v_cvt_pk_bf16_f32 v146, v202, v203
	v_cvt_pk_bf16_f32 v147, v204, v205
	s_nop 0
	v_lshl_add_u64 v[148:149], s[6:7], 0, v[148:149]
	v_lshl_add_u64 v[148:149], v[206:207], 1, v[148:149]
	v_readlane_b32 s5, v253, 17
	v_readlane_b32 s8, v253, 20
	v_readlane_b32 s9, v253, 21
	v_readlane_b32 s10, v253, 22
	v_readlane_b32 s11, v253, 23
	v_readlane_b32 s12, v253, 24
	v_readlane_b32 s13, v253, 25
	v_readlane_b32 s14, v253, 26
	v_readlane_b32 s15, v253, 27
	v_readlane_b32 s16, v253, 28
	v_readlane_b32 s17, v253, 29
	v_readlane_b32 s18, v253, 30
	v_readlane_b32 s19, v253, 31
	global_store_dwordx4 v[148:149], v[144:147], off
.LBB0_116:
	s_waitcnt vmcnt(12)
	v_lshlrev_b32_e32 v207, 16, v180
	v_and_b32_e32 v180, 0xffff0000, v180
	v_lshlrev_b32_e32 v144, 16, v176
	v_and_b32_e32 v145, 0xffff0000, v176
	v_lshlrev_b32_e32 v146, 16, v177
	v_and_b32_e32 v147, 0xffff0000, v177
	v_rcp_f32_e32 v176, v207
	v_rcp_f32_e32 v177, v180
	v_lshlrev_b32_e32 v210, 16, v181
	v_and_b32_e32 v181, 0xffff0000, v181
	v_lshlrev_b32_e32 v211, 16, v182
	v_pk_mul_f32 v[144:145], v[176:177], v[144:145]
	v_and_b32_e32 v182, 0xffff0000, v182
	v_cndmask_b32_e64 v145, v145, v177, s[36:37]
	v_cndmask_b32_e64 v144, v144, v176, s[36:37]
	v_pk_mul_f32 v[176:177], v[136:137], v[144:145]
	v_rcp_f32_e32 v136, v210
	v_rcp_f32_e32 v137, v181
	v_lshlrev_b32_e32 v148, 16, v178
	v_and_b32_e32 v149, 0xffff0000, v178
	v_lshlrev_b32_e32 v150, 16, v179
	v_pk_mul_f32 v[144:145], v[136:137], v[146:147]
	v_and_b32_e32 v151, 0xffff0000, v179
	v_cndmask_b32_e64 v137, v145, v137, s[36:37]
	v_cndmask_b32_e64 v136, v144, v136, s[36:37]
	v_pk_mul_f32 v[178:179], v[138:139], v[136:137]
	v_rcp_f32_e32 v136, v211
	v_rcp_f32_e32 v137, v182
	v_lshlrev_b32_e32 v212, 16, v183
	v_and_b32_e32 v183, 0xffff0000, v183
	s_andn2_b64 vcc, exec, s[36:37]
	v_pk_mul_f32 v[138:139], v[136:137], v[148:149]
	s_nop 0
	v_cndmask_b32_e64 v137, v139, v137, s[36:37]
	v_cndmask_b32_e64 v136, v138, v136, s[36:37]
	v_pk_mul_f32 v[180:181], v[128:129], v[136:137]
	v_rcp_f32_e32 v128, v212
	v_rcp_f32_e32 v129, v183
	s_nop 0
	v_pk_mul_f32 v[136:137], v[128:129], v[150:151]
	s_nop 0
	v_cndmask_b32_e64 v129, v137, v129, s[36:37]
	v_cndmask_b32_e64 v128, v136, v128, s[36:37]
	v_pk_mul_f32 v[182:183], v[130:131], v[128:129]
	v_cndmask_b32_e64 v128, 0, 1, s[36:37]
	v_cmp_ne_u32_e64 s[38:39], 1, v128
	v_or_b32_e32 v128, 16, v242
	v_lshl_add_u32 v214, s52, 8, v128
	s_cbranch_vccnz .LBB0_118
	v_ashrrev_i32_e32 v215, 31, v214
	v_readlane_b32 s4, v253, 16
	v_lshlrev_b64 v[136:137], 11, v[214:215]
	v_readlane_b32 s6, v253, 18
	v_readlane_b32 s7, v253, 19
	v_ashrrev_i32_e32 v207, 31, v206
	v_cvt_pk_bf16_f32 v128, v176, v177
	v_cvt_pk_bf16_f32 v129, v178, v179
	v_cvt_pk_bf16_f32 v130, v180, v181
	v_cvt_pk_bf16_f32 v131, v182, v183
	s_nop 0
	v_lshl_add_u64 v[136:137], s[6:7], 0, v[136:137]
	v_lshl_add_u64 v[136:137], v[206:207], 1, v[136:137]
	v_readlane_b32 s5, v253, 17
	v_readlane_b32 s8, v253, 20
	v_readlane_b32 s9, v253, 21
	v_readlane_b32 s10, v253, 22
	v_readlane_b32 s11, v253, 23
	v_readlane_b32 s12, v253, 24
	v_readlane_b32 s13, v253, 25
	v_readlane_b32 s14, v253, 26
	v_readlane_b32 s15, v253, 27
	v_readlane_b32 s16, v253, 28
	v_readlane_b32 s17, v253, 29
	v_readlane_b32 s18, v253, 30
	v_readlane_b32 s19, v253, 31
	global_store_dwordx4 v[136:137], v[128:131], off
.LBB0_118:
	s_waitcnt vmcnt(9)
	v_lshlrev_b32_e32 v144, 16, v168
	v_and_b32_e32 v145, 0xffff0000, v168
	v_rcp_f32_e32 v144, v144
	v_rcp_f32_e32 v145, v145
	v_lshlrev_b32_e32 v128, 16, v172
	v_and_b32_e32 v129, 0xffff0000, v172
	v_lshlrev_b32_e32 v146, 16, v169
	v_pk_mul_f32 v[128:129], v[144:145], v[128:129]
	v_and_b32_e32 v147, 0xffff0000, v169
	v_cndmask_b32_e64 v129, v129, v145, s[36:37]
	v_cndmask_b32_e64 v128, v128, v144, s[36:37]
	v_pk_mul_f32 v[168:169], v[124:125], v[128:129]
	v_rcp_f32_e32 v124, v146
	v_rcp_f32_e32 v125, v147
	v_lshlrev_b32_e32 v130, 16, v173
	v_and_b32_e32 v131, 0xffff0000, v173
	v_lshlrev_b32_e32 v148, 16, v170
	v_pk_mul_f32 v[128:129], v[124:125], v[130:131]
	v_and_b32_e32 v149, 0xffff0000, v170
	v_cndmask_b32_e64 v125, v129, v125, s[36:37]
	v_cndmask_b32_e64 v124, v128, v124, s[36:37]
	v_lshlrev_b32_e32 v150, 16, v171
	v_and_b32_e32 v151, 0xffff0000, v171
	v_pk_mul_f32 v[170:171], v[126:127], v[124:125]
	v_rcp_f32_e32 v124, v148
	v_rcp_f32_e32 v125, v149
	v_lshlrev_b32_e32 v136, 16, v174
	v_and_b32_e32 v137, 0xffff0000, v174
	v_lshlrev_b32_e32 v138, 16, v175
	v_pk_mul_f32 v[126:127], v[124:125], v[136:137]
	v_and_b32_e32 v139, 0xffff0000, v175
	v_cndmask_b32_e64 v125, v127, v125, s[36:37]
	v_cndmask_b32_e64 v124, v126, v124, s[36:37]
	v_pk_mul_f32 v[172:173], v[112:113], v[124:125]
	v_rcp_f32_e32 v112, v150
	v_rcp_f32_e32 v113, v151
	s_and_b64 vcc, exec, s[38:39]
	v_pk_mul_f32 v[124:125], v[112:113], v[138:139]
	s_nop 0
	v_cndmask_b32_e64 v113, v125, v113, s[36:37]
	v_cndmask_b32_e64 v112, v124, v112, s[36:37]
	v_pk_mul_f32 v[174:175], v[114:115], v[112:113]
	v_or_b32_e32 v112, 32, v242
	v_lshl_add_u32 v212, s52, 8, v112
	s_cbranch_vccnz .LBB0_120
	v_ashrrev_i32_e32 v213, 31, v212
	v_readlane_b32 s4, v253, 16
	v_lshlrev_b64 v[124:125], 11, v[212:213]
	v_readlane_b32 s6, v253, 18
	v_readlane_b32 s7, v253, 19
	v_ashrrev_i32_e32 v207, 31, v206
	v_cvt_pk_bf16_f32 v112, v168, v169
	v_cvt_pk_bf16_f32 v113, v170, v171
	v_cvt_pk_bf16_f32 v114, v172, v173
	v_cvt_pk_bf16_f32 v115, v174, v175
	s_nop 0
	v_lshl_add_u64 v[124:125], s[6:7], 0, v[124:125]
	v_lshl_add_u64 v[124:125], v[206:207], 1, v[124:125]
	v_readlane_b32 s5, v253, 17
	v_readlane_b32 s8, v253, 20
	v_readlane_b32 s9, v253, 21
	v_readlane_b32 s10, v253, 22
	v_readlane_b32 s11, v253, 23
	v_readlane_b32 s12, v253, 24
	v_readlane_b32 s13, v253, 25
	v_readlane_b32 s14, v253, 26
	v_readlane_b32 s15, v253, 27
	v_readlane_b32 s16, v253, 28
	v_readlane_b32 s17, v253, 29
	v_readlane_b32 s18, v253, 30
	v_readlane_b32 s19, v253, 31
	global_store_dwordx4 v[124:125], v[112:115], off
.LBB0_120:
	s_waitcnt vmcnt(5)
	v_lshlrev_b32_e32 v128, 16, v164
	v_and_b32_e32 v129, 0xffff0000, v164
	v_rcp_f32_e32 v128, v128
	v_rcp_f32_e32 v129, v129
	v_lshlrev_b32_e32 v112, 16, v160
	v_and_b32_e32 v113, 0xffff0000, v160
	v_lshlrev_b32_e32 v130, 16, v165
	v_pk_mul_f32 v[112:113], v[128:129], v[112:113]
	v_and_b32_e32 v131, 0xffff0000, v165
	v_cndmask_b32_e64 v113, v113, v129, s[36:37]
	v_cndmask_b32_e64 v112, v112, v128, s[36:37]
	v_lshlrev_b32_e32 v114, 16, v161
	v_and_b32_e32 v115, 0xffff0000, v161
	v_pk_mul_f32 v[160:161], v[108:109], v[112:113]
	v_rcp_f32_e32 v108, v130
	v_rcp_f32_e32 v109, v131
	v_lshlrev_b32_e32 v136, 16, v166
	v_and_b32_e32 v137, 0xffff0000, v166
	v_lshlrev_b32_e32 v124, 16, v162
	v_pk_mul_f32 v[112:113], v[108:109], v[114:115]
	v_and_b32_e32 v125, 0xffff0000, v162
	v_cndmask_b32_e64 v109, v113, v109, s[36:37]
	v_cndmask_b32_e64 v108, v112, v108, s[36:37]
	v_lshlrev_b32_e32 v126, 16, v163
	v_and_b32_e32 v127, 0xffff0000, v163
	v_pk_mul_f32 v[162:163], v[110:111], v[108:109]
	v_rcp_f32_e32 v108, v136
	v_rcp_f32_e32 v109, v137
	v_lshlrev_b32_e32 v138, 16, v167
	v_and_b32_e32 v139, 0xffff0000, v167
	s_and_b64 vcc, exec, s[38:39]
	v_pk_mul_f32 v[110:111], v[108:109], v[124:125]
	v_lshl_add_u32 v210, s52, 8, v246
	v_cndmask_b32_e64 v109, v111, v109, s[36:37]
	v_cndmask_b32_e64 v108, v110, v108, s[36:37]
	v_pk_mul_f32 v[164:165], v[96:97], v[108:109]
	v_rcp_f32_e32 v96, v138
	v_rcp_f32_e32 v97, v139
	s_nop 0
	v_pk_mul_f32 v[108:109], v[96:97], v[126:127]
	s_nop 0
	v_cndmask_b32_e64 v97, v109, v97, s[36:37]
	v_cndmask_b32_e64 v96, v108, v96, s[36:37]
	v_pk_mul_f32 v[166:167], v[98:99], v[96:97]
	s_cbranch_vccnz .LBB0_122
	v_ashrrev_i32_e32 v211, 31, v210
	v_readlane_b32 s4, v253, 16
	v_lshlrev_b64 v[108:109], 11, v[210:211]
	v_readlane_b32 s6, v253, 18
	v_readlane_b32 s7, v253, 19
	v_ashrrev_i32_e32 v207, 31, v206
	v_cvt_pk_bf16_f32 v96, v160, v161
	v_cvt_pk_bf16_f32 v97, v162, v163
	v_cvt_pk_bf16_f32 v98, v164, v165
	v_cvt_pk_bf16_f32 v99, v166, v167
	s_nop 0
	v_lshl_add_u64 v[108:109], s[6:7], 0, v[108:109]
	v_lshl_add_u64 v[108:109], v[206:207], 1, v[108:109]
	v_readlane_b32 s5, v253, 17
	v_readlane_b32 s8, v253, 20
	v_readlane_b32 s9, v253, 21
	v_readlane_b32 s10, v253, 22
	v_readlane_b32 s11, v253, 23
	v_readlane_b32 s12, v253, 24
	v_readlane_b32 s13, v253, 25
	v_readlane_b32 s14, v253, 26
	v_readlane_b32 s15, v253, 27
	v_readlane_b32 s16, v253, 28
	v_readlane_b32 s17, v253, 29
	v_readlane_b32 s18, v253, 30
	v_readlane_b32 s19, v253, 31
	global_store_dwordx4 v[108:109], v[96:99], off
.LBB0_122:
	s_mov_b64 s[22:23], 0x100000
	s_nop 0
	v_lshl_add_u64 v[96:97], v[208:209], 0, s[22:23]
	v_add_co_u32_e32 v98, vcc, 0x100000, v208
	v_lshl_add_u64 v[96:97], v[96:97], 0, s[88:89]
	s_nop 0
	v_addc_co_u32_e32 v99, vcc, 0, v209, vcc
	s_mov_b64 s[22:23], 0x120000
	global_load_dwordx4 v[144:147], v[98:99], off
	global_load_dwordx4 v[148:151], v[96:97], off
	v_lshl_add_u64 v[96:97], v[208:209], 0, s[22:23]
	v_add_co_u32_e32 v98, vcc, 0x120000, v208
	v_lshl_add_u64 v[96:97], v[96:97], 0, s[88:89]
	s_nop 0
	v_addc_co_u32_e32 v99, vcc, 0, v209, vcc
	s_mov_b64 s[22:23], 0x140000
	global_load_dwordx4 v[128:131], v[98:99], off
	global_load_dwordx4 v[136:139], v[96:97], off
	v_lshl_add_u64 v[96:97], v[208:209], 0, s[22:23]
	v_add_co_u32_e32 v98, vcc, 0x140000, v208
	v_lshl_add_u64 v[96:97], v[96:97], 0, s[88:89]
	s_nop 0
	v_addc_co_u32_e32 v99, vcc, 0, v209, vcc
	s_mov_b64 s[22:23], 0x160000
	global_load_dwordx4 v[112:115], v[98:99], off
	global_load_dwordx4 v[124:127], v[96:97], off
	v_lshl_add_u64 v[108:109], v[208:209], 0, s[22:23]
	v_add_co_u32_e32 v96, vcc, 0x160000, v208
	v_lshl_add_u64 v[108:109], v[108:109], 0, s[88:89]
	s_nop 0
	v_addc_co_u32_e32 v97, vcc, 0, v209, vcc
	global_load_dwordx4 v[96:99], v[96:97], off
	s_waitcnt vmcnt(10)
	v_lshlrev_b32_e32 v207, 16, v156
	global_load_dwordx4 v[108:111], v[108:109], off
	v_and_b32_e32 v211, 0xffff0000, v156
	v_lshlrev_b32_e32 v213, 16, v157
	v_and_b32_e32 v215, 0xffff0000, v157
	v_lshlrev_b32_e32 v217, 16, v158
	v_and_b32_e32 v251, 0xffff0000, v158
	v_lshlrev_b32_e32 v252, 16, v159
	v_and_b32_e32 v234, 0xffff0000, v159
	v_lshlrev_b32_e32 v156, 16, v152
	v_and_b32_e32 v157, 0xffff0000, v152
	v_lshlrev_b32_e32 v158, 16, v153
	v_and_b32_e32 v159, 0xffff0000, v153
	v_rcp_f32_e32 v152, v207
	v_rcp_f32_e32 v153, v211
	v_lshlrev_b32_e32 v230, 16, v154
	v_and_b32_e32 v231, 0xffff0000, v154
	v_lshlrev_b32_e32 v232, 16, v155
	v_and_b32_e32 v233, 0xffff0000, v155
	v_pk_mul_f32 v[154:155], v[152:153], v[156:157]
	s_and_b64 vcc, exec, s[38:39]
	v_cndmask_b32_e64 v153, v155, v153, s[36:37]
	v_cndmask_b32_e64 v152, v154, v152, s[36:37]
	v_pk_mul_f32 v[152:153], v[92:93], v[152:153]
	v_rcp_f32_e32 v92, v213
	v_rcp_f32_e32 v93, v215
	s_nop 0
	v_pk_mul_f32 v[154:155], v[92:93], v[158:159]
	s_nop 0
	v_cndmask_b32_e64 v93, v155, v93, s[36:37]
	v_cndmask_b32_e64 v92, v154, v92, s[36:37]
	v_pk_mul_f32 v[154:155], v[94:95], v[92:93]
	v_rcp_f32_e32 v92, v217
	v_rcp_f32_e32 v93, v251
	s_nop 0
	v_pk_mul_f32 v[94:95], v[92:93], v[230:231]
	s_nop 0
	v_cndmask_b32_e64 v93, v95, v93, s[36:37]
	v_cndmask_b32_e64 v92, v94, v92, s[36:37]
	v_pk_mul_f32 v[156:157], v[88:89], v[92:93]
	v_rcp_f32_e32 v88, v252
	v_rcp_f32_e32 v89, v234
	s_nop 0
	v_pk_mul_f32 v[92:93], v[88:89], v[232:233]
	s_nop 0
	v_cndmask_b32_e64 v89, v93, v89, s[36:37]
	v_cndmask_b32_e64 v88, v92, v88, s[36:37]
	v_pk_mul_f32 v[158:159], v[90:91], v[88:89]
	s_cbranch_vccnz .LBB0_124
	s_lshl_b32 s22, s55, 8
	v_ashrrev_i32_e32 v217, 31, v216
	v_readlane_b32 s4, v253, 16
	v_lshlrev_b64 v[92:93], 11, v[216:217]
	v_readlane_b32 s6, v253, 18
	v_readlane_b32 s7, v253, 19
	s_ashr_i32 s23, s22, 31
	v_mov_b32_e32 v95, s23
	v_lshl_add_u64 v[92:93], s[6:7], 0, v[92:93]
	v_or_b32_e32 v94, s22, v192
	v_lshl_add_u64 v[92:93], v[94:95], 1, v[92:93]
	v_cvt_pk_bf16_f32 v88, v152, v153
	v_cvt_pk_bf16_f32 v89, v154, v155
	v_cvt_pk_bf16_f32 v90, v156, v157
	v_cvt_pk_bf16_f32 v91, v158, v159
	v_readlane_b32 s5, v253, 17
	v_readlane_b32 s8, v253, 20
	v_readlane_b32 s9, v253, 21
	v_readlane_b32 s10, v253, 22
	v_readlane_b32 s11, v253, 23
	v_readlane_b32 s12, v253, 24
	v_readlane_b32 s13, v253, 25
	v_readlane_b32 s14, v253, 26
	v_readlane_b32 s15, v253, 27
	v_readlane_b32 s16, v253, 28
	v_readlane_b32 s17, v253, 29
	v_readlane_b32 s18, v253, 30
	v_readlane_b32 s19, v253, 31
	global_store_dwordx4 v[92:93], v[88:91], off offset:256

.LBB0_126:
	s_waitcnt vmcnt(10)
	v_lshlrev_b32_e32 v88, 16, v120
	v_and_b32_e32 v89, 0xffff0000, v120
	v_rcp_f32_e32 v88, v88
	v_rcp_f32_e32 v89, v89
	v_lshlrev_b32_e32 v80, 16, v116
	v_and_b32_e32 v81, 0xffff0000, v116
	v_lshlrev_b32_e32 v90, 16, v121
	v_pk_mul_f32 v[80:81], v[88:89], v[80:81]
	v_and_b32_e32 v91, 0xffff0000, v121
	v_cndmask_b32_e64 v81, v81, v89, s[36:37]
	v_cndmask_b32_e64 v80, v80, v88, s[36:37]
	v_lshlrev_b32_e32 v82, 16, v117
	v_and_b32_e32 v83, 0xffff0000, v117
	v_pk_mul_f32 v[116:117], v[76:77], v[80:81]
	v_rcp_f32_e32 v76, v90
	v_rcp_f32_e32 v77, v91
	v_lshlrev_b32_e32 v92, 16, v122
	v_and_b32_e32 v93, 0xffff0000, v122
	v_lshlrev_b32_e32 v84, 16, v118
	v_pk_mul_f32 v[80:81], v[76:77], v[82:83]
	v_and_b32_e32 v85, 0xffff0000, v118
	v_cndmask_b32_e64 v77, v81, v77, s[36:37]
	v_cndmask_b32_e64 v76, v80, v76, s[36:37]
	v_lshlrev_b32_e32 v86, 16, v119
	v_and_b32_e32 v87, 0xffff0000, v119
	v_pk_mul_f32 v[118:119], v[78:79], v[76:77]
	v_rcp_f32_e32 v76, v92
	v_rcp_f32_e32 v77, v93
	v_lshlrev_b32_e32 v94, 16, v123
	v_and_b32_e32 v95, 0xffff0000, v123
	s_and_b64 vcc, exec, s[38:39]
	v_pk_mul_f32 v[78:79], v[76:77], v[84:85]
	s_nop 0
	v_cndmask_b32_e64 v77, v79, v77, s[36:37]
	v_cndmask_b32_e64 v76, v78, v76, s[36:37]
	v_pk_mul_f32 v[120:121], v[72:73], v[76:77]
	v_rcp_f32_e32 v72, v94
	v_rcp_f32_e32 v73, v95
	s_nop 0
	v_pk_mul_f32 v[76:77], v[72:73], v[86:87]
	s_nop 0
	v_cndmask_b32_e64 v73, v77, v73, s[36:37]
	v_cndmask_b32_e64 v72, v76, v72, s[36:37]
	v_pk_mul_f32 v[122:123], v[74:75], v[72:73]
	s_cbranch_vccnz .LBB0_128
	s_lshl_b32 s22, s55, 8
	v_ashrrev_i32_e32 v213, 31, v212
	v_readlane_b32 s4, v253, 16
	v_lshlrev_b64 v[76:77], 11, v[212:213]
	v_readlane_b32 s6, v253, 18
	v_readlane_b32 s7, v253, 19
	s_ashr_i32 s23, s22, 31
	v_mov_b32_e32 v79, s23
	v_lshl_add_u64 v[76:77], s[6:7], 0, v[76:77]
	v_or_b32_e32 v78, s22, v192
	v_lshl_add_u64 v[76:77], v[78:79], 1, v[76:77]
	v_cvt_pk_bf16_f32 v72, v116, v117
	v_cvt_pk_bf16_f32 v73, v118, v119
	v_cvt_pk_bf16_f32 v74, v120, v121
	v_cvt_pk_bf16_f32 v75, v122, v123
	v_readlane_b32 s5, v253, 17
	v_readlane_b32 s8, v253, 20
	v_readlane_b32 s9, v253, 21
	v_readlane_b32 s10, v253, 22
	v_readlane_b32 s11, v253, 23
	v_readlane_b32 s12, v253, 24
	v_readlane_b32 s13, v253, 25
	v_readlane_b32 s14, v253, 26
	v_readlane_b32 s15, v253, 27
	v_readlane_b32 s16, v253, 28
	v_readlane_b32 s17, v253, 29
	v_readlane_b32 s18, v253, 30
	v_readlane_b32 s19, v253, 31
	global_store_dwordx4 v[76:77], v[72:75], off offset:256
.LBB0_128:
	s_waitcnt vmcnt(8)
	v_lshlrev_b32_e32 v80, 16, v104
	v_and_b32_e32 v81, 0xffff0000, v104
	v_rcp_f32_e32 v80, v80
	v_rcp_f32_e32 v81, v81
	v_lshlrev_b32_e32 v72, 16, v100
	v_and_b32_e32 v73, 0xffff0000, v100
	v_lshlrev_b32_e32 v82, 16, v105
	v_pk_mul_f32 v[72:73], v[80:81], v[72:73]
	v_and_b32_e32 v83, 0xffff0000, v105
	v_cndmask_b32_e64 v73, v73, v81, s[36:37]
	v_cndmask_b32_e64 v72, v72, v80, s[36:37]
	v_lshlrev_b32_e32 v74, 16, v101
	v_and_b32_e32 v75, 0xffff0000, v101
	v_pk_mul_f32 v[100:101], v[68:69], v[72:73]
	v_rcp_f32_e32 v68, v82
	v_rcp_f32_e32 v69, v83
	v_lshlrev_b32_e32 v84, 16, v106
	v_and_b32_e32 v85, 0xffff0000, v106
	v_lshlrev_b32_e32 v76, 16, v102
	v_pk_mul_f32 v[72:73], v[68:69], v[74:75]
	v_and_b32_e32 v77, 0xffff0000, v102
	v_cndmask_b32_e64 v69, v73, v69, s[36:37]
	v_cndmask_b32_e64 v68, v72, v68, s[36:37]
	v_lshlrev_b32_e32 v78, 16, v103
	v_and_b32_e32 v79, 0xffff0000, v103
	v_pk_mul_f32 v[102:103], v[70:71], v[68:69]
	v_rcp_f32_e32 v68, v84
	v_rcp_f32_e32 v69, v85
	v_lshlrev_b32_e32 v86, 16, v107
	v_and_b32_e32 v87, 0xffff0000, v107
	s_and_b64 vcc, exec, s[38:39]
	v_pk_mul_f32 v[70:71], v[68:69], v[76:77]
	s_nop 0
	v_cndmask_b32_e64 v69, v71, v69, s[36:37]
	v_cndmask_b32_e64 v68, v70, v68, s[36:37]
	v_pk_mul_f32 v[104:105], v[64:65], v[68:69]
	v_rcp_f32_e32 v64, v86
	v_rcp_f32_e32 v65, v87
	s_nop 0
	v_pk_mul_f32 v[68:69], v[64:65], v[78:79]
	s_nop 0
	v_cndmask_b32_e64 v65, v69, v65, s[36:37]
	v_cndmask_b32_e64 v64, v68, v64, s[36:37]
	v_pk_mul_f32 v[106:107], v[66:67], v[64:65]
	s_cbranch_vccnz .LBB0_130
	s_lshl_b32 s22, s55, 8
	v_ashrrev_i32_e32 v211, 31, v210
	v_readlane_b32 s4, v253, 16
	v_lshlrev_b64 v[68:69], 11, v[210:211]
	v_readlane_b32 s6, v253, 18
	v_readlane_b32 s7, v253, 19
	s_ashr_i32 s23, s22, 31
	v_mov_b32_e32 v71, s23
	v_lshl_add_u64 v[68:69], s[6:7], 0, v[68:69]
	v_or_b32_e32 v70, s22, v192
	v_lshl_add_u64 v[68:69], v[70:71], 1, v[68:69]
	v_cvt_pk_bf16_f32 v64, v100, v101
	v_cvt_pk_bf16_f32 v65, v102, v103
	v_cvt_pk_bf16_f32 v66, v104, v105
	v_cvt_pk_bf16_f32 v67, v106, v107
	v_readlane_b32 s5, v253, 17
	v_readlane_b32 s8, v253, 20
	v_readlane_b32 s9, v253, 21
	v_readlane_b32 s10, v253, 22
	v_readlane_b32 s11, v253, 23
	v_readlane_b32 s12, v253, 24
	v_readlane_b32 s13, v253, 25
	v_readlane_b32 s14, v253, 26
	v_readlane_b32 s15, v253, 27
	v_readlane_b32 s16, v253, 28
	v_readlane_b32 s17, v253, 29
	v_readlane_b32 s18, v253, 30
	v_readlane_b32 s19, v253, 31
	global_store_dwordx4 v[68:69], v[64:67], off offset:256
.LBB0_130:
	s_mov_b64 s[22:23], 0x101000
	s_nop 0
	v_lshl_add_u64 v[64:65], v[208:209], 0, s[22:23]
	v_add_co_u32_e32 v66, vcc, 0x101000, v208
	v_lshl_add_u64 v[64:65], v[64:65], 0, s[88:89]
	s_nop 0
	v_addc_co_u32_e32 v67, vcc, 0, v209, vcc
	s_mov_b64 s[22:23], 0x121000
	global_load_dwordx4 v[88:91], v[66:67], off
	global_load_dwordx4 v[92:95], v[64:65], off
	v_lshl_add_u64 v[64:65], v[208:209], 0, s[22:23]
	v_add_co_u32_e32 v66, vcc, 0x121000, v208
	v_lshl_add_u64 v[64:65], v[64:65], 0, s[88:89]
	s_nop 0
	v_addc_co_u32_e32 v67, vcc, 0, v209, vcc
	s_mov_b64 s[22:23], 0x141000
	global_load_dwordx4 v[80:83], v[66:67], off
	global_load_dwordx4 v[84:87], v[64:65], off
	v_lshl_add_u64 v[64:65], v[208:209], 0, s[22:23]
	v_add_co_u32_e32 v66, vcc, 0x141000, v208
	v_lshl_add_u64 v[64:65], v[64:65], 0, s[88:89]
	s_nop 0
	v_addc_co_u32_e32 v67, vcc, 0, v209, vcc
	s_mov_b64 s[22:23], 0x161000
	global_load_dwordx4 v[72:75], v[66:67], off
	global_load_dwordx4 v[76:79], v[64:65], off
	v_lshl_add_u64 v[68:69], v[208:209], 0, s[22:23]
	v_add_co_u32_e32 v64, vcc, 0x161000, v208
	v_lshl_add_u64 v[68:69], v[68:69], 0, s[88:89]
	s_nop 0
	v_addc_co_u32_e32 v65, vcc, 0, v209, vcc
	global_load_dwordx4 v[64:67], v[64:65], off
	s_waitcnt vmcnt(13)
	v_lshlrev_b32_e32 v207, 16, v144
	global_load_dwordx4 v[68:71], v[68:69], off
	v_and_b32_e32 v209, 0xffff0000, v144
	v_rcp_f32_e32 v208, v207
	v_rcp_f32_e32 v209, v209
	v_lshlrev_b32_e32 v210, 16, v145
	v_and_b32_e32 v211, 0xffff0000, v145
	v_lshlrev_b32_e32 v144, 16, v148
	v_and_b32_e32 v145, 0xffff0000, v148
	v_pk_mul_f32 v[144:145], v[208:209], v[144:145]
	v_lshlrev_b32_e32 v212, 16, v146
	v_cndmask_b32_e64 v145, v145, v209, s[36:37]
	v_cndmask_b32_e64 v144, v144, v208, s[36:37]
	v_pk_mul_f32 v[60:61], v[60:61], v[144:145]
	v_rcp_f32_e32 v144, v210
	v_rcp_f32_e32 v145, v211
	v_and_b32_e32 v213, 0xffff0000, v146
	v_lshlrev_b32_e32 v214, 16, v147
	v_and_b32_e32 v215, 0xffff0000, v147
	v_lshlrev_b32_e32 v146, 16, v149
	v_and_b32_e32 v147, 0xffff0000, v149
	v_pk_mul_f32 v[146:147], v[144:145], v[146:147]
	v_lshlrev_b32_e32 v148, 16, v150
	v_cndmask_b32_e64 v145, v147, v145, s[36:37]
	v_cndmask_b32_e64 v144, v146, v144, s[36:37]
	v_pk_mul_f32 v[62:63], v[62:63], v[144:145]
	v_rcp_f32_e32 v144, v212
	v_rcp_f32_e32 v145, v213
	v_and_b32_e32 v149, 0xffff0000, v150
	v_lshlrev_b32_e32 v150, 16, v151
	v_and_b32_e32 v151, 0xffff0000, v151
	v_pk_mul_f32 v[146:147], v[144:145], v[148:149]
	s_and_b64 vcc, exec, s[38:39]
	v_cndmask_b32_e64 v145, v147, v145, s[36:37]
	v_cndmask_b32_e64 v144, v146, v144, s[36:37]
	v_pk_mul_f32 v[56:57], v[56:57], v[144:145]
	v_rcp_f32_e32 v144, v214
	v_rcp_f32_e32 v145, v215
	s_nop 0
	v_pk_mul_f32 v[146:147], v[144:145], v[150:151]
	s_nop 0
	v_cndmask_b32_e64 v145, v147, v145, s[36:37]
	v_cndmask_b32_e64 v144, v146, v144, s[36:37]
	v_pk_mul_f32 v[58:59], v[58:59], v[144:145]
	v_lshl_add_u32 v144, s52, 8, v247
	s_cbranch_vccnz .LBB0_132
	v_ashrrev_i32_e32 v145, 31, v144
	v_readlane_b32 s4, v253, 16
	v_lshlrev_b64 v[150:151], 11, v[144:145]
	v_readlane_b32 s6, v253, 18
	v_readlane_b32 s7, v253, 19
	v_ashrrev_i32_e32 v207, 31, v206
	v_cvt_pk_bf16_f32 v146, v60, v61
	v_cvt_pk_bf16_f32 v147, v62, v63
	v_cvt_pk_bf16_f32 v148, v56, v57
	v_cvt_pk_bf16_f32 v149, v58, v59
	s_nop 0
	v_lshl_add_u64 v[150:151], s[6:7], 0, v[150:151]
	v_lshl_add_u64 v[150:151], v[206:207], 1, v[150:151]
	v_readlane_b32 s5, v253, 17
	v_readlane_b32 s8, v253, 20
	v_readlane_b32 s9, v253, 21
	v_readlane_b32 s10, v253, 22
	v_readlane_b32 s11, v253, 23
	v_readlane_b32 s12, v253, 24
	v_readlane_b32 s13, v253, 25
	v_readlane_b32 s14, v253, 26
	v_readlane_b32 s15, v253, 27
	v_readlane_b32 s16, v253, 28
	v_readlane_b32 s17, v253, 29
	v_readlane_b32 s18, v253, 30
	v_readlane_b32 s19, v253, 31
	global_store_dwordx4 v[150:151], v[146:149], off
.LBB0_132:
	s_waitcnt vmcnt(12)
	v_lshlrev_b32_e32 v145, 16, v128
	s_nop 0
	v_and_b32_e32 v147, 0xffff0000, v128
	v_rcp_f32_e32 v146, v145
	v_rcp_f32_e32 v147, v147
	v_lshlrev_b32_e32 v148, 16, v129
	v_and_b32_e32 v149, 0xffff0000, v129
	v_lshlrev_b32_e32 v128, 16, v136
	v_and_b32_e32 v129, 0xffff0000, v136
	v_pk_mul_f32 v[128:129], v[146:147], v[128:129]
	v_lshlrev_b32_e32 v150, 16, v130
	v_cndmask_b32_e64 v129, v129, v147, s[36:37]
	v_cndmask_b32_e64 v128, v128, v146, s[36:37]
	v_pk_mul_f32 v[52:53], v[52:53], v[128:129]
	v_rcp_f32_e32 v128, v148
	v_rcp_f32_e32 v129, v149
	v_and_b32_e32 v151, 0xffff0000, v130
	v_lshlrev_b32_e32 v207, 16, v131
	v_and_b32_e32 v208, 0xffff0000, v131
	v_lshlrev_b32_e32 v130, 16, v137
	v_and_b32_e32 v131, 0xffff0000, v137
	v_pk_mul_f32 v[130:131], v[128:129], v[130:131]
	v_lshlrev_b32_e32 v136, 16, v138
	v_cndmask_b32_e64 v129, v131, v129, s[36:37]
	v_cndmask_b32_e64 v128, v130, v128, s[36:37]
	v_pk_mul_f32 v[54:55], v[54:55], v[128:129]
	v_rcp_f32_e32 v128, v150
	v_rcp_f32_e32 v129, v151
	v_and_b32_e32 v137, 0xffff0000, v138
	v_lshlrev_b32_e32 v138, 16, v139
	v_and_b32_e32 v139, 0xffff0000, v139
	v_pk_mul_f32 v[130:131], v[128:129], v[136:137]
	s_and_b64 vcc, exec, s[38:39]
	v_cndmask_b32_e64 v129, v131, v129, s[36:37]
	v_cndmask_b32_e64 v128, v130, v128, s[36:37]
	v_pk_mul_f32 v[48:49], v[48:49], v[128:129]
	v_rcp_f32_e32 v128, v207
	v_rcp_f32_e32 v129, v208
	s_nop 0
	v_pk_mul_f32 v[130:131], v[128:129], v[138:139]
	s_nop 0
	v_cndmask_b32_e64 v129, v131, v129, s[36:37]
	v_cndmask_b32_e64 v128, v130, v128, s[36:37]
	v_pk_mul_f32 v[50:51], v[50:51], v[128:129]
	v_lshl_add_u32 v128, s52, 8, v248
	s_cbranch_vccnz .LBB0_134
	v_ashrrev_i32_e32 v129, 31, v128
	v_readlane_b32 s4, v253, 16
	v_lshlrev_b64 v[130:131], 11, v[128:129]
	v_readlane_b32 s6, v253, 18
	v_readlane_b32 s7, v253, 19
	v_ashrrev_i32_e32 v207, 31, v206
	v_cvt_pk_bf16_f32 v136, v52, v53
	v_cvt_pk_bf16_f32 v137, v54, v55
	v_cvt_pk_bf16_f32 v138, v48, v49
	v_cvt_pk_bf16_f32 v139, v50, v51
	s_nop 0
	v_lshl_add_u64 v[130:131], s[6:7], 0, v[130:131]
	v_lshl_add_u64 v[130:131], v[206:207], 1, v[130:131]
	v_readlane_b32 s5, v253, 17
	v_readlane_b32 s8, v253, 20
	v_readlane_b32 s9, v253, 21
	v_readlane_b32 s10, v253, 22
	v_readlane_b32 s11, v253, 23
	v_readlane_b32 s12, v253, 24
	v_readlane_b32 s13, v253, 25
	v_readlane_b32 s14, v253, 26
	v_readlane_b32 s15, v253, 27
	v_readlane_b32 s16, v253, 28
	v_readlane_b32 s17, v253, 29
	v_readlane_b32 s18, v253, 30
	v_readlane_b32 s19, v253, 31
	global_store_dwordx4 v[130:131], v[136:139], off
.LBB0_134:
	s_waitcnt vmcnt(10)
	v_lshlrev_b32_e32 v129, 16, v112
	v_and_b32_e32 v131, 0xffff0000, v112
	v_rcp_f32_e32 v130, v129
	v_rcp_f32_e32 v131, v131
	v_lshlrev_b32_e32 v136, 16, v113
	v_and_b32_e32 v137, 0xffff0000, v113
	v_lshlrev_b32_e32 v112, 16, v124
	v_and_b32_e32 v113, 0xffff0000, v124
	v_pk_mul_f32 v[112:113], v[130:131], v[112:113]
	v_lshlrev_b32_e32 v138, 16, v114
	v_cndmask_b32_e64 v113, v113, v131, s[36:37]
	v_cndmask_b32_e64 v112, v112, v130, s[36:37]
	v_pk_mul_f32 v[44:45], v[44:45], v[112:113]
	v_rcp_f32_e32 v112, v136
	v_rcp_f32_e32 v113, v137
	v_and_b32_e32 v139, 0xffff0000, v114
	v_lshlrev_b32_e32 v145, 16, v115
	v_and_b32_e32 v146, 0xffff0000, v115
	v_lshlrev_b32_e32 v114, 16, v125
	v_and_b32_e32 v115, 0xffff0000, v125
	v_pk_mul_f32 v[114:115], v[112:113], v[114:115]
	v_lshlrev_b32_e32 v124, 16, v126
	v_cndmask_b32_e64 v113, v115, v113, s[36:37]
	v_cndmask_b32_e64 v112, v114, v112, s[36:37]
	v_pk_mul_f32 v[46:47], v[46:47], v[112:113]
	v_rcp_f32_e32 v112, v138
	v_rcp_f32_e32 v113, v139
	v_and_b32_e32 v125, 0xffff0000, v126
	v_lshlrev_b32_e32 v126, 16, v127
	v_and_b32_e32 v127, 0xffff0000, v127
	v_pk_mul_f32 v[114:115], v[112:113], v[124:125]
	s_and_b64 vcc, exec, s[38:39]
	v_cndmask_b32_e64 v113, v115, v113, s[36:37]
	v_cndmask_b32_e64 v112, v114, v112, s[36:37]
	v_pk_mul_f32 v[40:41], v[40:41], v[112:113]
	v_rcp_f32_e32 v112, v145
	v_rcp_f32_e32 v113, v146
	s_nop 0
	v_pk_mul_f32 v[114:115], v[112:113], v[126:127]
	s_nop 0
	v_cndmask_b32_e64 v113, v115, v113, s[36:37]
	v_cndmask_b32_e64 v112, v114, v112, s[36:37]
	v_pk_mul_f32 v[42:43], v[42:43], v[112:113]
	v_lshl_add_u32 v112, s52, 8, v249
	s_cbranch_vccnz .LBB0_136
	v_ashrrev_i32_e32 v113, 31, v112
	v_readlane_b32 s4, v253, 16
	v_lshlrev_b64 v[114:115], 11, v[112:113]
	v_readlane_b32 s6, v253, 18
	v_readlane_b32 s7, v253, 19
	v_ashrrev_i32_e32 v207, 31, v206
	v_cvt_pk_bf16_f32 v124, v44, v45
	v_cvt_pk_bf16_f32 v125, v46, v47
	v_cvt_pk_bf16_f32 v126, v40, v41
	v_cvt_pk_bf16_f32 v127, v42, v43
	s_nop 0
	v_lshl_add_u64 v[114:115], s[6:7], 0, v[114:115]
	v_lshl_add_u64 v[114:115], v[206:207], 1, v[114:115]
	v_readlane_b32 s5, v253, 17
	v_readlane_b32 s8, v253, 20
	v_readlane_b32 s9, v253, 21
	v_readlane_b32 s10, v253, 22
	v_readlane_b32 s11, v253, 23
	v_readlane_b32 s12, v253, 24
	v_readlane_b32 s13, v253, 25
	v_readlane_b32 s14, v253, 26
	v_readlane_b32 s15, v253, 27
	v_readlane_b32 s16, v253, 28
	v_readlane_b32 s17, v253, 29
	v_readlane_b32 s18, v253, 30
	v_readlane_b32 s19, v253, 31
	global_store_dwordx4 v[114:115], v[124:127], off
.LBB0_136:
	s_waitcnt vmcnt(8)
	v_lshlrev_b32_e32 v113, 16, v96
	v_and_b32_e32 v115, 0xffff0000, v96
	v_rcp_f32_e32 v114, v113
	v_rcp_f32_e32 v115, v115
	v_lshlrev_b32_e32 v124, 16, v97
	v_and_b32_e32 v125, 0xffff0000, v97
	v_lshlrev_b32_e32 v96, 16, v108
	v_and_b32_e32 v97, 0xffff0000, v108
	v_pk_mul_f32 v[96:97], v[114:115], v[96:97]
	v_lshlrev_b32_e32 v126, 16, v98
	v_cndmask_b32_e64 v97, v97, v115, s[36:37]
	v_cndmask_b32_e64 v96, v96, v114, s[36:37]
	v_pk_mul_f32 v[36:37], v[36:37], v[96:97]
	v_rcp_f32_e32 v96, v124
	v_rcp_f32_e32 v97, v125
	v_and_b32_e32 v127, 0xffff0000, v98
	v_lshlrev_b32_e32 v129, 16, v99
	v_and_b32_e32 v130, 0xffff0000, v99
	v_lshlrev_b32_e32 v98, 16, v109
	v_and_b32_e32 v99, 0xffff0000, v109
	v_pk_mul_f32 v[98:99], v[96:97], v[98:99]
	v_lshlrev_b32_e32 v108, 16, v110
	v_cndmask_b32_e64 v97, v99, v97, s[36:37]
	v_cndmask_b32_e64 v96, v98, v96, s[36:37]
	v_pk_mul_f32 v[38:39], v[38:39], v[96:97]
	v_rcp_f32_e32 v96, v126
	v_rcp_f32_e32 v97, v127
	v_and_b32_e32 v109, 0xffff0000, v110
	v_lshlrev_b32_e32 v110, 16, v111
	v_and_b32_e32 v111, 0xffff0000, v111
	v_pk_mul_f32 v[98:99], v[96:97], v[108:109]
	s_and_b64 vcc, exec, s[38:39]
	v_cndmask_b32_e64 v97, v99, v97, s[36:37]
	v_cndmask_b32_e64 v96, v98, v96, s[36:37]
	v_pk_mul_f32 v[32:33], v[32:33], v[96:97]
	v_rcp_f32_e32 v96, v129
	v_rcp_f32_e32 v97, v130
	s_nop 0
	v_pk_mul_f32 v[98:99], v[96:97], v[110:111]
	s_nop 0
	v_cndmask_b32_e64 v97, v99, v97, s[36:37]
	v_cndmask_b32_e64 v96, v98, v96, s[36:37]
	v_pk_mul_f32 v[34:35], v[34:35], v[96:97]
	v_lshl_add_u32 v96, s52, 8, v250
	s_cbranch_vccnz .LBB0_138
	v_ashrrev_i32_e32 v97, 31, v96
	v_readlane_b32 s4, v253, 16
	v_lshlrev_b64 v[98:99], 11, v[96:97]
	v_readlane_b32 s6, v253, 18
	v_readlane_b32 s7, v253, 19
	v_ashrrev_i32_e32 v207, 31, v206
	v_cvt_pk_bf16_f32 v108, v36, v37
	v_cvt_pk_bf16_f32 v109, v38, v39
	v_cvt_pk_bf16_f32 v110, v32, v33
	v_cvt_pk_bf16_f32 v111, v34, v35
	s_nop 0
	v_lshl_add_u64 v[98:99], s[6:7], 0, v[98:99]
	v_lshl_add_u64 v[98:99], v[206:207], 1, v[98:99]
	v_readlane_b32 s5, v253, 17
	v_readlane_b32 s8, v253, 20
	v_readlane_b32 s9, v253, 21
	v_readlane_b32 s10, v253, 22
	v_readlane_b32 s11, v253, 23
	v_readlane_b32 s12, v253, 24
	v_readlane_b32 s13, v253, 25
	v_readlane_b32 s14, v253, 26
	v_readlane_b32 s15, v253, 27
	v_readlane_b32 s16, v253, 28
	v_readlane_b32 s17, v253, 29
	v_readlane_b32 s18, v253, 30
	v_readlane_b32 s19, v253, 31
	global_store_dwordx4 v[98:99], v[108:111], off
.LBB0_138:
	s_waitcnt vmcnt(6)
	v_lshlrev_b32_e32 v97, 16, v88
	v_and_b32_e32 v99, 0xffff0000, v88
	v_rcp_f32_e32 v98, v97
	v_rcp_f32_e32 v99, v99
	v_lshlrev_b32_e32 v108, 16, v89
	v_and_b32_e32 v109, 0xffff0000, v89
	v_lshlrev_b32_e32 v88, 16, v92
	v_and_b32_e32 v89, 0xffff0000, v92
	v_pk_mul_f32 v[88:89], v[98:99], v[88:89]
	v_lshlrev_b32_e32 v110, 16, v90
	v_cndmask_b32_e64 v89, v89, v99, s[36:37]
	v_cndmask_b32_e64 v88, v88, v98, s[36:37]
	v_pk_mul_f32 v[28:29], v[28:29], v[88:89]
	v_rcp_f32_e32 v88, v108
	v_rcp_f32_e32 v89, v109
	v_and_b32_e32 v111, 0xffff0000, v90
	v_lshlrev_b32_e32 v113, 16, v91
	v_and_b32_e32 v114, 0xffff0000, v91
	v_lshlrev_b32_e32 v90, 16, v93
	v_and_b32_e32 v91, 0xffff0000, v93
	v_pk_mul_f32 v[90:91], v[88:89], v[90:91]
	v_lshlrev_b32_e32 v92, 16, v94
	v_cndmask_b32_e64 v89, v91, v89, s[36:37]
	v_cndmask_b32_e64 v88, v90, v88, s[36:37]
	v_pk_mul_f32 v[30:31], v[30:31], v[88:89]
	v_rcp_f32_e32 v88, v110
	v_rcp_f32_e32 v89, v111
	v_and_b32_e32 v93, 0xffff0000, v94
	v_lshlrev_b32_e32 v94, 16, v95
	v_and_b32_e32 v95, 0xffff0000, v95
	v_pk_mul_f32 v[90:91], v[88:89], v[92:93]
	s_and_b64 vcc, exec, s[38:39]
	v_cndmask_b32_e64 v89, v91, v89, s[36:37]
	v_cndmask_b32_e64 v88, v90, v88, s[36:37]
	v_pk_mul_f32 v[24:25], v[24:25], v[88:89]
	v_rcp_f32_e32 v88, v113
	v_rcp_f32_e32 v89, v114
	s_nop 0
	v_pk_mul_f32 v[90:91], v[88:89], v[94:95]
	s_nop 0
	v_cndmask_b32_e64 v89, v91, v89, s[36:37]
	v_cndmask_b32_e64 v88, v90, v88, s[36:37]
	v_pk_mul_f32 v[26:27], v[26:27], v[88:89]
	s_cbranch_vccnz .LBB0_140
	s_lshl_b32 s22, s55, 8
	v_ashrrev_i32_e32 v145, 31, v144
	v_readlane_b32 s4, v253, 16
	v_lshlrev_b64 v[92:93], 11, v[144:145]
	v_readlane_b32 s6, v253, 18
	v_readlane_b32 s7, v253, 19
	s_ashr_i32 s23, s22, 31
	v_mov_b32_e32 v95, s23
	v_lshl_add_u64 v[92:93], s[6:7], 0, v[92:93]
	v_or_b32_e32 v94, s22, v192
	v_lshl_add_u64 v[92:93], v[94:95], 1, v[92:93]
	v_cvt_pk_bf16_f32 v88, v28, v29
	v_cvt_pk_bf16_f32 v89, v30, v31
	v_cvt_pk_bf16_f32 v90, v24, v25
	v_cvt_pk_bf16_f32 v91, v26, v27
	v_readlane_b32 s5, v253, 17
	v_readlane_b32 s8, v253, 20
	v_readlane_b32 s9, v253, 21
	v_readlane_b32 s10, v253, 22
	v_readlane_b32 s11, v253, 23
	v_readlane_b32 s12, v253, 24
	v_readlane_b32 s13, v253, 25
	v_readlane_b32 s14, v253, 26
	v_readlane_b32 s15, v253, 27
	v_readlane_b32 s16, v253, 28
	v_readlane_b32 s17, v253, 29
	v_readlane_b32 s18, v253, 30
	v_readlane_b32 s19, v253, 31
	global_store_dwordx4 v[92:93], v[88:91], off offset:256
.LBB0_140:
	s_waitcnt vmcnt(4)
	s_nop 1
	v_lshlrev_b32_e32 v88, 16, v80
	v_and_b32_e32 v89, 0xffff0000, v80
	v_rcp_f32_e32 v88, v88
	v_rcp_f32_e32 v89, v89
	v_lshlrev_b32_e32 v90, 16, v81
	v_and_b32_e32 v91, 0xffff0000, v81
	v_lshlrev_b32_e32 v80, 16, v84
	v_and_b32_e32 v81, 0xffff0000, v84
	v_pk_mul_f32 v[80:81], v[88:89], v[80:81]
	v_lshlrev_b32_e32 v92, 16, v82
	v_cndmask_b32_e64 v81, v81, v89, s[36:37]
	v_cndmask_b32_e64 v80, v80, v88, s[36:37]
	v_pk_mul_f32 v[20:21], v[20:21], v[80:81]
	v_rcp_f32_e32 v80, v90
	v_rcp_f32_e32 v81, v91
	v_and_b32_e32 v93, 0xffff0000, v82
	v_lshlrev_b32_e32 v94, 16, v83
	v_and_b32_e32 v95, 0xffff0000, v83
	v_lshlrev_b32_e32 v82, 16, v85
	v_and_b32_e32 v83, 0xffff0000, v85
	v_pk_mul_f32 v[82:83], v[80:81], v[82:83]
	v_lshlrev_b32_e32 v84, 16, v86
	v_cndmask_b32_e64 v81, v83, v81, s[36:37]
	v_cndmask_b32_e64 v80, v82, v80, s[36:37]
	v_pk_mul_f32 v[22:23], v[22:23], v[80:81]
	v_rcp_f32_e32 v80, v92
	v_rcp_f32_e32 v81, v93
	v_and_b32_e32 v85, 0xffff0000, v86
	v_lshlrev_b32_e32 v86, 16, v87
	v_and_b32_e32 v87, 0xffff0000, v87
	v_pk_mul_f32 v[82:83], v[80:81], v[84:85]
	s_and_b64 vcc, exec, s[38:39]
	v_cndmask_b32_e64 v81, v83, v81, s[36:37]
	v_cndmask_b32_e64 v80, v82, v80, s[36:37]
	v_pk_mul_f32 v[16:17], v[16:17], v[80:81]
	v_rcp_f32_e32 v80, v94
	v_rcp_f32_e32 v81, v95
	s_nop 0
	v_pk_mul_f32 v[82:83], v[80:81], v[86:87]
	s_nop 0
	v_cndmask_b32_e64 v81, v83, v81, s[36:37]
	v_cndmask_b32_e64 v80, v82, v80, s[36:37]
	v_pk_mul_f32 v[18:19], v[18:19], v[80:81]
	s_cbranch_vccnz .LBB0_142
	s_lshl_b32 s22, s55, 8
	v_ashrrev_i32_e32 v129, 31, v128
	v_readlane_b32 s4, v253, 16
	v_lshlrev_b64 v[84:85], 11, v[128:129]
	v_readlane_b32 s6, v253, 18
	v_readlane_b32 s7, v253, 19
	s_ashr_i32 s23, s22, 31
	v_mov_b32_e32 v87, s23
	v_lshl_add_u64 v[84:85], s[6:7], 0, v[84:85]
	v_or_b32_e32 v86, s22, v192
	v_lshl_add_u64 v[84:85], v[86:87], 1, v[84:85]
	v_cvt_pk_bf16_f32 v80, v20, v21
	v_cvt_pk_bf16_f32 v81, v22, v23
	v_cvt_pk_bf16_f32 v82, v16, v17
	v_cvt_pk_bf16_f32 v83, v18, v19
	v_readlane_b32 s5, v253, 17
	v_readlane_b32 s8, v253, 20
	v_readlane_b32 s9, v253, 21
	v_readlane_b32 s10, v253, 22
	v_readlane_b32 s11, v253, 23
	v_readlane_b32 s12, v253, 24
	v_readlane_b32 s13, v253, 25
	v_readlane_b32 s14, v253, 26
	v_readlane_b32 s15, v253, 27
	v_readlane_b32 s16, v253, 28
	v_readlane_b32 s17, v253, 29
	v_readlane_b32 s18, v253, 30
	v_readlane_b32 s19, v253, 31
	global_store_dwordx4 v[84:85], v[80:83], off offset:256
.LBB0_142:
	s_waitcnt vmcnt(2)
	s_nop 1
	v_lshlrev_b32_e32 v80, 16, v72
	v_and_b32_e32 v81, 0xffff0000, v72
	v_rcp_f32_e32 v80, v80
	v_rcp_f32_e32 v81, v81
	v_lshlrev_b32_e32 v82, 16, v73
	v_and_b32_e32 v83, 0xffff0000, v73
	v_lshlrev_b32_e32 v72, 16, v76
	v_and_b32_e32 v73, 0xffff0000, v76
	v_pk_mul_f32 v[72:73], v[80:81], v[72:73]
	v_lshlrev_b32_e32 v84, 16, v74
	v_cndmask_b32_e64 v73, v73, v81, s[36:37]
	v_cndmask_b32_e64 v72, v72, v80, s[36:37]
	v_pk_mul_f32 v[12:13], v[12:13], v[72:73]
	v_rcp_f32_e32 v72, v82
	v_rcp_f32_e32 v73, v83
	v_and_b32_e32 v85, 0xffff0000, v74
	v_lshlrev_b32_e32 v86, 16, v75
	v_and_b32_e32 v87, 0xffff0000, v75
	v_lshlrev_b32_e32 v74, 16, v77
	v_and_b32_e32 v75, 0xffff0000, v77
	v_pk_mul_f32 v[74:75], v[72:73], v[74:75]
	v_lshlrev_b32_e32 v76, 16, v78
	v_cndmask_b32_e64 v73, v75, v73, s[36:37]
	v_cndmask_b32_e64 v72, v74, v72, s[36:37]
	v_pk_mul_f32 v[14:15], v[14:15], v[72:73]
	v_rcp_f32_e32 v72, v84
	v_rcp_f32_e32 v73, v85
	v_and_b32_e32 v77, 0xffff0000, v78
	v_lshlrev_b32_e32 v78, 16, v79
	v_and_b32_e32 v79, 0xffff0000, v79
	v_pk_mul_f32 v[74:75], v[72:73], v[76:77]
	s_and_b64 vcc, exec, s[38:39]
	v_cndmask_b32_e64 v73, v75, v73, s[36:37]
	v_cndmask_b32_e64 v72, v74, v72, s[36:37]
	v_pk_mul_f32 v[4:5], v[4:5], v[72:73]
	v_rcp_f32_e32 v72, v86
	v_rcp_f32_e32 v73, v87
	s_nop 0
	v_pk_mul_f32 v[74:75], v[72:73], v[78:79]
	s_nop 0
	v_cndmask_b32_e64 v73, v75, v73, s[36:37]
	v_cndmask_b32_e64 v72, v74, v72, s[36:37]
	v_pk_mul_f32 v[6:7], v[6:7], v[72:73]
	s_cbranch_vccnz .LBB0_144
	s_lshl_b32 s22, s55, 8
	v_ashrrev_i32_e32 v113, 31, v112
	v_readlane_b32 s4, v253, 16
	v_lshlrev_b64 v[76:77], 11, v[112:113]
	v_readlane_b32 s6, v253, 18
	v_readlane_b32 s7, v253, 19
	s_ashr_i32 s23, s22, 31
	v_mov_b32_e32 v79, s23
	v_lshl_add_u64 v[76:77], s[6:7], 0, v[76:77]
	v_or_b32_e32 v78, s22, v192
	v_lshl_add_u64 v[76:77], v[78:79], 1, v[76:77]
	v_cvt_pk_bf16_f32 v72, v12, v13
	v_cvt_pk_bf16_f32 v73, v14, v15
	v_cvt_pk_bf16_f32 v74, v4, v5
	v_cvt_pk_bf16_f32 v75, v6, v7
	v_readlane_b32 s5, v253, 17
	v_readlane_b32 s8, v253, 20
	v_readlane_b32 s9, v253, 21
	v_readlane_b32 s10, v253, 22
	v_readlane_b32 s11, v253, 23
	v_readlane_b32 s12, v253, 24
	v_readlane_b32 s13, v253, 25
	v_readlane_b32 s14, v253, 26
	v_readlane_b32 s15, v253, 27
	v_readlane_b32 s16, v253, 28
	v_readlane_b32 s17, v253, 29
	v_readlane_b32 s18, v253, 30
	v_readlane_b32 s19, v253, 31
	global_store_dwordx4 v[76:77], v[72:75], off offset:256
.LBB0_144:
	s_waitcnt vmcnt(1)
	s_nop 1
	v_lshlrev_b32_e32 v72, 16, v64
	v_and_b32_e32 v73, 0xffff0000, v64
	v_rcp_f32_e32 v72, v72
	v_rcp_f32_e32 v73, v73
	v_lshlrev_b32_e32 v74, 16, v65
	v_and_b32_e32 v75, 0xffff0000, v65
	s_waitcnt vmcnt(0)
	v_lshlrev_b32_e32 v64, 16, v68
	v_and_b32_e32 v65, 0xffff0000, v68
	v_pk_mul_f32 v[64:65], v[72:73], v[64:65]
	v_lshlrev_b32_e32 v76, 16, v66
	v_cndmask_b32_e64 v65, v65, v73, s[36:37]
	v_cndmask_b32_e64 v64, v64, v72, s[36:37]
	v_pk_mul_f32 v[8:9], v[8:9], v[64:65]
	v_rcp_f32_e32 v64, v74
	v_rcp_f32_e32 v65, v75
	v_and_b32_e32 v77, 0xffff0000, v66
	v_lshlrev_b32_e32 v78, 16, v67
	v_and_b32_e32 v79, 0xffff0000, v67
	v_lshlrev_b32_e32 v66, 16, v69
	v_and_b32_e32 v67, 0xffff0000, v69
	v_pk_mul_f32 v[66:67], v[64:65], v[66:67]
	v_lshlrev_b32_e32 v68, 16, v70
	v_cndmask_b32_e64 v65, v67, v65, s[36:37]
	v_cndmask_b32_e64 v64, v66, v64, s[36:37]
	v_pk_mul_f32 v[10:11], v[10:11], v[64:65]
	v_rcp_f32_e32 v64, v76
	v_rcp_f32_e32 v65, v77
	v_and_b32_e32 v69, 0xffff0000, v70
	v_lshlrev_b32_e32 v70, 16, v71
	v_and_b32_e32 v71, 0xffff0000, v71
	v_pk_mul_f32 v[66:67], v[64:65], v[68:69]
	s_and_b64 vcc, exec, s[38:39]
	v_cndmask_b32_e64 v65, v67, v65, s[36:37]
	v_cndmask_b32_e64 v64, v66, v64, s[36:37]
	v_pk_mul_f32 v[0:1], v[0:1], v[64:65]
	v_rcp_f32_e32 v64, v78
	v_rcp_f32_e32 v65, v79
	s_nop 0
	v_pk_mul_f32 v[66:67], v[64:65], v[70:71]
	s_nop 0
	v_cndmask_b32_e64 v65, v67, v65, s[36:37]
	v_cndmask_b32_e64 v64, v66, v64, s[36:37]
	v_pk_mul_f32 v[2:3], v[2:3], v[64:65]
	s_cbranch_vccnz .LBB0_107
	s_lshl_b32 s22, s55, 8
	v_ashrrev_i32_e32 v97, 31, v96
	v_readlane_b32 s4, v253, 16
	v_lshlrev_b64 v[68:69], 11, v[96:97]
	v_readlane_b32 s6, v253, 18
	v_readlane_b32 s7, v253, 19
	s_ashr_i32 s23, s22, 31
	v_mov_b32_e32 v71, s23
	v_lshl_add_u64 v[68:69], s[6:7], 0, v[68:69]
	v_or_b32_e32 v70, s22, v192
	v_lshl_add_u64 v[68:69], v[70:71], 1, v[68:69]
	v_cvt_pk_bf16_f32 v64, v8, v9
	v_cvt_pk_bf16_f32 v65, v10, v11
	v_cvt_pk_bf16_f32 v66, v0, v1
	v_cvt_pk_bf16_f32 v67, v2, v3
	v_readlane_b32 s5, v253, 17
	v_readlane_b32 s8, v253, 20
	v_readlane_b32 s9, v253, 21
	v_readlane_b32 s10, v253, 22
	v_readlane_b32 s11, v253, 23
	v_readlane_b32 s12, v253, 24
	v_readlane_b32 s13, v253, 25
	v_readlane_b32 s14, v253, 26
	v_readlane_b32 s15, v253, 27
	v_readlane_b32 s16, v253, 28
	v_readlane_b32 s17, v253, 29
	v_readlane_b32 s18, v253, 30
	v_readlane_b32 s19, v253, 31
	global_store_dwordx4 v[68:69], v[64:67], off offset:256
	s_branch .LBB0_107
